# S5 matrix generation moved out of phase A: 16 CUs run it beside the in-projection GEMM, which now uses 240 CUs x 13 tiles; attention epilogue sub-LN weights prefetched
# speedup vs baseline: 1.0106x; 1.0106x over previous
; __global__ void __launch_bounds__(512, 2) mega_fwd(Params P) {
;     ...
;             for (int t = c; t < 256; t += G)
;                 s5_gen_task(lds, t >> 2, t & 3, PIN(I_S5LR) + l * 4096, PIN(I_S5LI) + l * 4096, PIN(I_S5BR) + (size_t)l * 65536, PIN(I_S5BI) + (size_t)l * 65536,
;                              PIN(I_S5CR) + (size_t)l * 65536, PIN(I_S5CI) + (size_t)l * 65536, PIN(I_S5LS) + l * 64, TPM, W1M);
.LBB0_75:
	s_or_b64 exec, exec, s[14:15]
	s_lshl_b32 s14, s24, 12
	s_mov_b32 s15, s69
	v_writelane_b32 v254, s14, 59
	s_barrier
	s_nop 0
	v_writelane_b32 v254, s15, 60
	s_lshl_b32 s14, s24, 6
	s_mov_b32 s15, s69
	v_writelane_b32 v254, s14, 61
	s_nop 1
	v_writelane_b32 v254, s15, 62
	v_readlane_b32 s14, v252, 5
	v_readlane_b32 s15, v252, 6
	s_andn2_b64 vcc, exec, s[14:15]
	s_nop 0
	v_cndmask_b32_e64 v0, 0, 1, s[14:15]
	v_cmp_ne_u32_e64 s[16:17], 1, v0
	s_nop 1
	v_writelane_b32 v254, s16, 63
	s_nop 1
	v_writelane_b32 v255, s17, 0
	s_branch .LBB0_130
.Ls5gen_entry:
	s_load_dwordx8 s[40:47], s[4:5], 0x70
	s_load_dwordx4 s[28:31], s[4:5], 0x90
	s_load_dwordx2 s[48:49], s[4:5], 0xa8
	v_readlane_b32 s4, v254, 59
	v_readlane_b32 s5, v254, 60
	s_lshl_b64 s[14:15], s[4:5], 2
	s_waitcnt lgkmcnt(0)
	s_add_u32 s4, s40, s14
	s_addc_u32 s5, s41, s15
	v_readlane_b32 s16, v254, 53
	s_add_u32 s14, s42, s14
	v_readlane_b32 s17, v254, 54
	s_addc_u32 s15, s43, s15
	s_lshl_b64 s[40:41], s[16:17], 18
	s_add_u32 s16, s44, s40
	s_addc_u32 s17, s45, s41
	s_add_u32 s18, s46, s40
	s_addc_u32 s19, s47, s41
	s_add_u32 s24, s28, s40
	s_addc_u32 s25, s29, s41
	s_add_u32 s28, s30, s40
	s_addc_u32 s29, s31, s41
	v_readlane_b32 s30, v254, 61
	v_readlane_b32 s31, v254, 62
	s_lshl_b64 s[30:31], s[30:31], 2
	s_add_u32 s50, s48, s30
	s_addc_u32 s51, s49, s31
	s_add_u32 s52, s34, 0x28500000
	s_addc_u32 s53, s35, 0
	s_add_u32 s54, s34, 0x2ad00000
	s_addc_u32 s55, s35, 0
	s_sub_u32 s56, s2, 0xf0
	s_sub_u32 s57, s2, 0xf0
	s_branch .LBB0_78
.LBB0_77:
	s_or_b64 exec, exec, s[40:41]
	s_add_i32 s57, s57, 16
	s_add_i32 s56, s56, 16
	s_cmpk_gt_i32 s57, 0xff
	s_barrier
	s_cbranch_scc1 .Ls5gen_ret

; #define LAS __attribute__((address_space(3)))
; #define PG8_STAGE(bufoff, gbase, voff) do { _Pragma("unroll") for (int _i = 0; _i < 2; ++_i) \
;         __builtin_amdgcn_global_load_lds((const unsigned*)((const char*)(gbase) + (voff)[_i]), (LAS unsigned*)(lds + (bufoff) + ldsw + _i * 8192), 16, 0, 0); } while (0)
; #define PG8_BAR __builtin_amdgcn_s_barrier()
; template <class Epi, class Sched>
; __device__ __forceinline__ void gemm_phase(LAS unsigned char* lds, const int lda, const int ldb, const Sched& S, const Epi& E) {
;     int tid_ = threadIdx.x; asm volatile("" : "+v"(tid_));
;     const int tid = tid_, wid = __builtin_amdgcn_readfirstlane(tid >> 6), lane = tid & 63, wr = wid >> 2, wc = wid & 3, fr = lane & 15, fq = lane >> 4;
;     unsigned voffA[2], voffB[2];
; #pragma unroll
;     for (int i = 0; i < 2; ++i) { int R, C; stage_rc(tid * 16 + i * 8192, R, C); const int Rb = Epi::PERM ? ((R & ~31) + perm32(R & 31)) : R;
;         voffA[i] = (unsigned)(R * lda + C) * 2u; voffB[i] = (unsigned)(Rb * ldb + C) * 2u; }
;     const size_t kstep = (size_t)(BK * 2);
;     const size_t hstepA = (size_t)HALF * lda * 2, hstepB = (size_t)HALF * ldb * 2;
;     const unsigned ldsw = (unsigned)wid * 1024u;
;     const int aoff = lds_byte(wr * 64 + fr, fq * 8), boff = lds_byte(wc * 32 + fr, fq * 8);
;     ...
;     Unit cur, nxt; int ui = 0;
;     if (!S.next(0, cur)) return;
;     f32x4 acc[2][2][4][2];
; #pragma unroll
;     for (int a = 0; a < 2; ++a)
; #pragma unroll
;         for (int b = 0; b < 2; ++b)
; #pragma unroll
;             for (int m = 0; m < 4; ++m)
; #pragma unroll
;                 for (int n = 0; n < 2; ++n) acc[a][b][m][n] = (f32x4){0.f, 0.f, 0.f, 0.f};
;     bf16x8 At[4][2], B0[2][2], B1[2][2];
;     const char* cA = cur.A; const char* cB = cur.B; asm volatile("" : "+s"(cA), "+s"(cB));
;     PG8_STAGE(PG8_SB(0, 0), cB, voffB); PG8_STAGE(PG8_SB(0, 1), cB + hstepB, voffB); PG8_STAGE(PG8_SA(0, 0), cA, voffA); PG8_STAGE(PG8_SA(0, 1), cA + hstepA, voffA);
;     if (wr == 1) PG8_BAR;
.LBB0_184:
	s_and_b64 vcc, exec, s[42:43]
	s_movk_i32 s42, 0x2000
	s_movk_i32 s43, 0x2080
	s_cbranch_vccnz .LBB0_360
	s_cmpk_lt_u32 s2, 0xf0
	s_cbranch_scc1 .Lg1_go
	v_writelane_b32 v255, s4, 8
	s_nop 1
	v_writelane_b32 v255, s5, 9
	s_nop 1
	v_writelane_b32 v255, s14, 10
	s_nop 1
	v_writelane_b32 v255, s15, 11
	s_nop 1
	v_writelane_b32 v255, s16, 12
	s_nop 1
	v_writelane_b32 v255, s17, 13
	s_nop 1
	v_writelane_b32 v255, s18, 14
	s_nop 1
	v_writelane_b32 v255, s19, 15
	s_nop 1
	v_writelane_b32 v255, s24, 16
	s_nop 1
	v_writelane_b32 v255, s25, 17
	s_nop 1
	v_writelane_b32 v255, s28, 18
	s_nop 1
	v_writelane_b32 v255, s29, 19
	s_nop 1
	v_writelane_b32 v255, s30, 20
	s_nop 1
	v_writelane_b32 v255, s31, 21
	s_nop 1
	v_writelane_b32 v255, s34, 22
	s_nop 1
	v_writelane_b32 v255, s35, 23
	s_nop 1
	v_writelane_b32 v255, s40, 24
	s_nop 1
	v_writelane_b32 v255, s41, 25
	s_nop 1
	v_writelane_b32 v255, s42, 26
	s_nop 1
	v_writelane_b32 v255, s43, 27
	s_nop 1
	v_writelane_b32 v255, s44, 28
	s_nop 1
	v_writelane_b32 v255, s45, 29
	s_nop 1
	v_writelane_b32 v255, s46, 30
	s_nop 1
	v_writelane_b32 v255, s47, 31
	s_nop 1
	v_writelane_b32 v255, s48, 32
	s_nop 1
	v_writelane_b32 v255, s49, 33
	s_nop 1
	v_writelane_b32 v255, s50, 34
	s_nop 1
	v_writelane_b32 v255, s51, 35
	s_nop 1
	v_writelane_b32 v255, s52, 36
	s_nop 1
	v_writelane_b32 v255, s53, 37
	s_nop 1
	v_writelane_b32 v255, s54, 38
	s_nop 1
	v_writelane_b32 v255, s55, 39
	s_nop 1
	v_writelane_b32 v255, s56, 40
	s_nop 1
	v_writelane_b32 v255, s57, 41
	s_nop 1
	v_writelane_b32 v255, s58, 42
	s_nop 1
	v_writelane_b32 v255, s59, 43
	s_nop 1
	v_readlane_b32 s4, v254, 30
	v_readlane_b32 s5, v254, 31
	v_readfirstlane_b32 s34, v162
	v_readfirstlane_b32 s35, v163
	s_nop 4
	s_branch .Ls5gen_entry
.Ls5gen_ret:
	s_mov_b64 exec, -1
	s_waitcnt vmcnt(0) lgkmcnt(0)
	v_readlane_b32 s4, v255, 8
	v_readlane_b32 s5, v255, 9
	v_readlane_b32 s14, v255, 10
	v_readlane_b32 s15, v255, 11
	v_readlane_b32 s16, v255, 12
	v_readlane_b32 s17, v255, 13
	v_readlane_b32 s18, v255, 14
	v_readlane_b32 s19, v255, 15
	v_readlane_b32 s24, v255, 16
	v_readlane_b32 s25, v255, 17
	v_readlane_b32 s28, v255, 18
	v_readlane_b32 s29, v255, 19
	v_readlane_b32 s30, v255, 20
	v_readlane_b32 s31, v255, 21
	v_readlane_b32 s34, v255, 22
	v_readlane_b32 s35, v255, 23
	v_readlane_b32 s40, v255, 24
	v_readlane_b32 s41, v255, 25
	v_readlane_b32 s42, v255, 26
	v_readlane_b32 s43, v255, 27
	v_readlane_b32 s44, v255, 28
	v_readlane_b32 s45, v255, 29
	v_readlane_b32 s46, v255, 30
	v_readlane_b32 s47, v255, 31
	v_readlane_b32 s48, v255, 32
	v_readlane_b32 s49, v255, 33
	v_readlane_b32 s50, v255, 34
	v_readlane_b32 s51, v255, 35
	v_readlane_b32 s52, v255, 36
	v_readlane_b32 s53, v255, 37
	v_readlane_b32 s54, v255, 38
	v_readlane_b32 s55, v255, 39
	v_readlane_b32 s56, v255, 40
	v_readlane_b32 s57, v255, 41
	v_readlane_b32 s58, v255, 42
	v_readlane_b32 s59, v255, 43
	s_nop 4
	s_branch .LBB0_360
.Lg1_go:
	v_ashrrev_i32_e32 v3, 31, v0
	v_lshrrev_b32_e32 v3, 26, v3
	v_add_u32_e32 v3, v0, v3
	v_ashrrev_i32_e32 v10, 6, v3
	v_bfe_i32 v3, v0, 27, 1
	v_lshlrev_b32_e32 v2, 4, v0
	v_lshrrev_b32_e32 v3, 22, v3
	v_add_u32_e32 v3, v2, v3
	v_and_b32_e32 v3, 0xfffffc00, v3
	v_sub_u32_e32 v3, v2, v3
	v_lshrrev_b32_e32 v4, 4, v3
	v_bitop3_b32 v3, v4, v3, 32 bitop3:0x6c
	v_ashrrev_i32_e32 v5, 31, v3
	v_lshrrev_b32_e32 v5, 26, v5
	v_add_u32_e32 v5, v3, v5
	v_lshlrev_b32_e32 v4, 3, v10
	v_ashrrev_i32_e32 v11, 6, v5
	v_and_b32_e32 v5, 0xc0, v5
	v_and_b32_e32 v4, -16, v4
	v_sub_u32_e32 v3, v3, v5
	v_mov_b32_e32 v8, 1
	v_add_u32_e32 v4, v11, v4
	v_ashrrev_i16_sdwa v3, v8, sext(v3) dst_sel:DWORD dst_unused:UNUSED_PAD src0_sel:DWORD src1_sel:BYTE_0
	v_lshlrev_b32_e32 v6, 5, v10
	v_bfe_i32 v12, v3, 0, 16
	v_lshlrev_b32_e32 v3, 1, v4
	v_lshrrev_b32_e32 v5, 2, v4
	v_and_b32_e32 v7, 3, v11
	s_mov_b32 s4, 0xfffe0
	v_and_b32_e32 v6, 32, v6
	v_and_b32_e32 v3, 24, v3
	v_and_b32_e32 v5, 4, v5
	v_and_or_b32 v7, v4, s4, v7
	v_or3_b32 v3, v7, v5, v3
	v_add_lshl_u32 v5, v6, v12, 1
	v_add_u32_e32 v2, 0x2000, v2
	v_lshl_add_u32 v148, v3, 12, v5
	v_ashrrev_i32_e32 v3, 31, v2
	v_lshrrev_b32_e32 v3, 22, v3
	v_add_u32_e32 v3, v2, v3
	v_ashrrev_i32_e32 v13, 10, v3
	v_mul_i32_i24_e32 v3, 0x400, v13
	v_sub_u32_e32 v2, v2, v3
	v_lshrrev_b32_e32 v3, 4, v2
	v_bitop3_b32 v2, v3, v2, 32 bitop3:0x6c
	v_lshl_add_u32 v146, v4, 12, v5
	v_ashrrev_i32_e32 v4, 31, v2
	v_lshrrev_b32_e32 v4, 26, v4
	v_add_u32_e32 v4, v2, v4
	v_lshlrev_b32_e32 v3, 3, v13
	v_ashrrev_i32_e32 v14, 6, v4
	v_and_b32_e32 v4, 0xc0, v4
	v_and_b32_e32 v3, -16, v3
	v_sub_u32_e32 v2, v2, v4
	s_ashr_i32 s34, s28, 6
	v_add_u32_e32 v3, v14, v3
	v_ashrrev_i16_sdwa v2, v8, sext(v2) dst_sel:DWORD dst_unused:UNUSED_PAD src0_sel:DWORD src1_sel:BYTE_0
	s_lshl_b32 s58, s34, 10
	v_lshlrev_b32_e32 v5, 5, v13
	v_bfe_i32 v15, v2, 0, 16
	v_lshlrev_b32_e32 v2, 1, v3
	v_lshrrev_b32_e32 v4, 2, v3
	v_and_b32_e32 v6, 3, v14
	s_add_i32 s59, s58, 0
	v_and_b32_e32 v5, 32, v5
	v_and_b32_e32 v2, 24, v2
	v_and_b32_e32 v4, 4, v4
	v_and_or_b32 v6, v3, s4, v6
	s_add_i32 m0, s59, 0x10000
	s_ashr_i32 s29, s28, 8
	v_or3_b32 v2, v6, v4, v2
	v_add_lshl_u32 v4, v5, v15, 1
	v_lshl_add_u32 v152, v2, 12, v4
	global_load_lds_dwordx4 v148, s[50:51]
	s_add_i32 m0, s59, 0x12000
	s_add_u32 s4, s50, 0x80000
	global_load_lds_dwordx4 v152, s[50:51]
	s_addc_u32 s5, s51, 0
	s_add_i32 m0, s59, 0x14000
	s_add_i32 s60, s59, 0x2000
	global_load_lds_dwordx4 v148, s[4:5]
	s_add_i32 m0, s59, 0x16000
	v_lshl_add_u32 v150, v3, 12, v4
	global_load_lds_dwordx4 v152, s[4:5]
	s_mov_b32 m0, s59
	s_add_u32 s4, s48, 0x80000
	global_load_lds_dwordx4 v146, s[48:49]
	s_mov_b32 m0, s60
	s_addc_u32 s5, s49, 0
	s_add_i32 s61, s59, 0x4000
	global_load_lds_dwordx4 v150, s[48:49]
	s_mov_b32 m0, s61
	s_add_i32 s68, s59, 0x6000
	global_load_lds_dwordx4 v146, s[4:5]
	s_mov_b32 m0, s68
	v_mov_b32_e32 v149, v1
	global_load_lds_dwordx4 v150, s[4:5]
	v_mov_b32_e32 v153, v1
	v_mov_b32_e32 v147, v1
	v_mov_b32_e32 v151, v1
	s_cmp_eq_u32 s29, 1
	v_lshl_add_u64 v[8:9], s[50:51], 0, v[148:149]
	v_lshl_add_u64 v[6:7], s[50:51], 0, v[152:153]
	v_lshl_add_u64 v[2:3], s[48:49], 0, v[146:147]
	s_cselect_b64 s[4:5], -1, 0
	s_cmp_lg_u32 s29, 1
	v_lshl_add_u64 v[4:5], s[48:49], 0, v[150:151]
	s_cbranch_scc1 .LBB0_187
	s_barrier

;     __device__ __forceinline__ bool next(int i, Unit& u) const {
;         const int L = i * G + c; if (L >= nM * nN) return false;
;         int pm, pn; dense_tile(L, nM, nN, pm, pn);
;         u.pm = pm; u.pn = pn; u.aux = 0; u.nt = ntk;
;         u.A = (const char*)(A + (size_t)pm * 256 * lda); u.B = (const char*)(Bt + (size_t)pn * 256 * ldb); return true;
.LBB0_190:
	s_add_i32 s75, s75, 1
	s_mul_i32 s35, s75, 0xf0
	s_add_i32 s35, s35, s2
	s_cmpk_lt_i32 s35, 0xc30
	s_cselect_b64 s[44:45], -1, 0
	s_cmpk_gt_i32 s35, 0xc2f
	s_cbranch_scc1 .LBB0_192
	s_ashr_i32 s34, s35, 31
	s_lshr_b32 s34, s34, 29
	s_add_i32 s34, s35, s34
	s_ashr_i32 s40, s34, 3
	s_and_b32 s34, s34, -8
	s_sub_i32 s34, s35, s34
	s_cmp_lt_i32 s34, 0
	s_movk_i32 s35, 0x187
	s_cselect_b32 s35, s35, 0x186
	s_mul_i32 s34, s34, s35
	s_add_i32 s34, s34, s40
	s_mul_hi_i32 s35, s34, 0x2aaaaaab
	s_lshr_b32 s40, s35, 31
	s_ashr_i32 s35, s35, 6
	s_add_i32 s35, s35, s40
	s_lshl_b32 s40, s35, 3
	s_sub_i32 s41, 0x41, s40
	s_min_u32 s41, s41, 8
	s_mulk_i32 s35, 0x180
	s_sub_i32 s43, s34, s35
	v_cvt_f32_ubyte0_e32 v2, s41
	v_cvt_f32_i32_e32 v0, s43
	v_rcp_iflag_f32_e32 v3, v2
	s_ashr_i32 s34, s43, 30
	s_or_b32 s42, s34, 1
	v_mul_f32_e32 v3, v0, v3
	v_trunc_f32_e32 v3, v3
	v_fma_f32 v0, -v3, v2, v0
	v_cvt_i32_f32_e32 v3, v3
	v_cmp_ge_f32_e64 s[34:35], |v0|, v2
	s_and_b64 s[34:35], s[34:35], exec
	s_cselect_b32 s34, s42, 0
	v_readfirstlane_b32 s35, v3
	s_add_i32 s42, s35, s34
	s_mul_i32 s34, s42, s41
	s_sub_i32 s34, s43, s34
	s_sext_i32_i16 s34, s34
	s_add_i32 s34, s40, s34
	s_ashr_i32 s35, s34, 31
	s_lshl_b64 s[40:41], s[34:35], 20
	s_add_u32 s40, s56, s40
	s_sext_i32_i16 s88, s42
	s_addc_u32 s41, s57, s41
	s_bfe_i64 s[42:43], s[42:43], 0x100000
	s_lshl_b64 s[42:43], s[42:43], 20
	s_add_u32 s46, s54, s42
	s_addc_u32 s47, s55, s43

; __device__ __forceinline__ unsigned cvt_pk_bf16(float lo, float hi) { unsigned r; asm volatile("v_cvt_pk_bf16_f32 %0, %1, %2" : "=v"(r) : "v"(lo), "v"(hi)); return r; }
; __device__ __forceinline__ void attn_phase(LAS unsigned char* lds, bf16_t* p5, const bf16_t* vt, const float* relb, const float* dalam, const float* subln, float lam_init, int ocol) {
;     ...
;         __syncthreads();
;         if (cc == 0) {
; #pragma unroll
;             for (int rg = 0; rg < 2; ++rg) { const int q = qrow0 + 16 * rg + lq; float ss = 0.f;
; #pragma unroll
;                 for (int k = 0; k < 8; ++k) { O[rg][k] -= xch[(rg * 8 + k) * 64]; ss += (O[rg][k].x * O[rg][k].x + O[rg][k].y * O[rg][k].y) + (O[rg][k].z * O[rg][k].z + O[rg][k].w * O[rg][k].w); }
;                 ss = rows4_sum(ss);
;                 const float rn = rsqrtf(ss * (1.0f / 128.0f) + 1e-5f) * (1.0f - lam_init);
;                 if (q < TP) {
; #pragma unroll
;                     for (int k = 0; k < 8; ++k) { const f32x4 w = *(const f32x4*)(subln + 16 * k + 4 * g4); const f32x4 o = O[rg][k] * rn * w;
;                         *(u32x2*)(p5 + ((size_t)b * TP + q) * LDP + ocol + h * 128 + 16 * k + 4 * g4) = (u32x2){cvt_pk_bf16(o.x, o.y), cvt_pk_bf16(o.z, o.w)}; }
;                 }
.LBB0_783:
	s_and_b64 vcc, exec, s[14:15]
	s_waitcnt lgkmcnt(0)
	s_barrier
	s_cbranch_vccz .LBB0_789
	global_load_dwordx4 v[76:79], v[144:145], off
	global_load_dwordx4 v[84:87], v[144:145], off offset:64
	global_load_dwordx4 v[96:99], v[144:145], off offset:128
	global_load_dwordx4 v[112:115], v[144:145], off offset:192
	global_load_dwordx4 v[116:119], v[144:145], off offset:256
	global_load_dwordx4 v[120:123], v[144:145], off offset:320
	global_load_dwordx4 v[124:127], v[144:145], off offset:384
	global_load_dwordx4 v[128:131], v[144:145], off offset:448
	ds_read_b128 v[34:37], v197
	ds_read_b128 v[46:49], v197 offset:2048
	ds_read_b128 v[60:63], v197 offset:6144
	ds_read_b128 v[64:67], v197 offset:7168
	v_cmp_gt_i32_e32 vcc, s73, v168
	s_waitcnt lgkmcnt(3)
	v_sub_f32_e32 v43, v111, v37
	v_sub_f32_e32 v42, v110, v36
	ds_read_b128 v[36:39], v197 offset:1024
	ds_read_b128 v[52:55], v197 offset:4096
	v_sub_f32_e32 v45, v109, v35
	v_sub_f32_e32 v44, v108, v34
	v_mul_f32_e32 v0, v45, v45
	v_mul_f32_e32 v34, v43, v43
	v_fmac_f32_e32 v0, v44, v44
	v_fmac_f32_e32 v34, v42, v42
	s_waitcnt lgkmcnt(1)
	v_sub_f32_e32 v35, v107, v39
	v_sub_f32_e32 v37, v105, v37
	v_add_f32_e32 v0, v0, v34
	v_sub_f32_e32 v34, v106, v38
	v_sub_f32_e32 v36, v104, v36
	v_mul_f32_e32 v38, v37, v37
	v_mul_f32_e32 v39, v35, v35
	v_fmac_f32_e32 v38, v36, v36
	v_fmac_f32_e32 v39, v34, v34
	v_add_f32_e32 v38, v38, v39
	v_add_f32_e32 v0, v0, v38
	v_sub_f32_e32 v39, v103, v49
	v_sub_f32_e32 v38, v102, v48
	ds_read_b128 v[48:51], v197 offset:3072
	ds_read_b128 v[56:59], v197 offset:5120
	v_sub_f32_e32 v41, v101, v47
	v_sub_f32_e32 v40, v100, v46
	v_mul_f32_e32 v46, v41, v41
	v_mul_f32_e32 v47, v39, v39
	v_fmac_f32_e32 v46, v40, v40
	v_fmac_f32_e32 v47, v38, v38
	v_add_f32_e32 v46, v46, v47
	s_waitcnt lgkmcnt(1)
	v_sub_f32_e32 v47, v95, v51
	v_sub_f32_e32 v49, v93, v49
	v_add_f32_e32 v0, v0, v46
	v_sub_f32_e32 v46, v94, v50
	v_sub_f32_e32 v48, v92, v48
	v_mul_f32_e32 v50, v49, v49
	v_mul_f32_e32 v51, v47, v47
	v_fmac_f32_e32 v50, v48, v48
	v_fmac_f32_e32 v51, v46, v46
	v_add_f32_e32 v50, v50, v51
	v_sub_f32_e32 v51, v91, v55
	v_sub_f32_e32 v53, v89, v53
	v_add_f32_e32 v0, v0, v50
	v_sub_f32_e32 v50, v90, v54
	v_sub_f32_e32 v52, v88, v52
	v_mul_f32_e32 v54, v53, v53
	v_mul_f32_e32 v55, v51, v51
	v_fmac_f32_e32 v54, v52, v52
	v_fmac_f32_e32 v55, v50, v50
	v_add_f32_e32 v54, v54, v55
	s_waitcnt lgkmcnt(0)
	v_sub_f32_e32 v55, v83, v59
	v_sub_f32_e32 v57, v81, v57
	v_add_f32_e32 v0, v0, v54
	v_sub_f32_e32 v54, v82, v58
	v_sub_f32_e32 v56, v80, v56
	v_mul_f32_e32 v58, v57, v57
	v_mul_f32_e32 v59, v55, v55
	v_fmac_f32_e32 v58, v56, v56
	v_fmac_f32_e32 v59, v54, v54
	v_add_f32_e32 v58, v58, v59
	v_sub_f32_e32 v59, v75, v63
	v_sub_f32_e32 v61, v73, v61
	v_add_f32_e32 v0, v0, v58
	v_sub_f32_e32 v58, v74, v62
	v_sub_f32_e32 v60, v72, v60
	v_mul_f32_e32 v62, v61, v61
	v_mul_f32_e32 v63, v59, v59
	v_fmac_f32_e32 v62, v60, v60
	v_fmac_f32_e32 v63, v58, v58
	v_add_f32_e32 v62, v62, v63
	v_sub_f32_e32 v63, v71, v67
	v_sub_f32_e32 v65, v69, v65
	v_add_f32_e32 v0, v0, v62
	v_sub_f32_e32 v62, v70, v66
	v_sub_f32_e32 v64, v68, v64
	v_mul_f32_e32 v66, v65, v65
	v_mul_f32_e32 v67, v63, v63
	v_fmac_f32_e32 v66, v64, v64
	v_fmac_f32_e32 v67, v62, v62
	v_add_f32_e32 v66, v66, v67
	v_add_f32_e32 v0, v0, v66
	v_mov_b32_e32 v66, v0
	s_nop 1
	v_permlane16_swap_b32_e32 v0, v66
	v_add_f32_e32 v66, v0, v66
	v_mov_b32_e32 v67, v66
	s_nop 1
	v_permlane32_swap_b32_e32 v66, v67
	v_lshlrev_b32_e32 v0, 1, v142
	s_and_saveexec_b64 s[28:29], vcc
	s_cbranch_execz .LBB0_786
	v_add_f32_e32 v66, v66, v67
	v_mov_b32_e32 v67, 0x3727c5ac
	v_fmamk_f32 v66, v66, 0x3c000000, v67
	s_mov_b32 s30, 0x800000
	v_cmp_gt_f32_e32 vcc, s30, v66
	v_mul_f32_e32 v67, 0x4b800000, v66
	v_ashrrev_i32_e32 v169, 31, v168
	v_cndmask_b32_e32 v66, v66, v67, vcc
	v_rsq_f32_e32 v66, v66
	v_mov_b64_e32 v[70:71], s[4:5]
	s_lshl_b32 s68, s19, 1
	v_mul_f32_e32 v67, 0x45800000, v66
	v_cndmask_b32_e32 v66, v66, v67, vcc
	v_mul_f32_e32 v68, v178, v66
	v_lshl_add_u64 v[66:67], v[168:169], 0, s[24:25]
	v_mad_u64_u32 v[70:71], s[30:31], v66, s84, v[70:71]
	v_mad_i32_i24 v71, v67, s84, v71
	v_lshl_add_u64 v[66:67], v[70:71], 0, s[68:69]
	s_nop 1
	v_lshl_add_u64 v[74:75], v[66:67], 0, v[0:1]
	s_mov_b64 s[30:31], 0x1000
	v_pk_mul_f32 v[44:45], v[44:45], v[68:69] op_sel_hi:[1,0]
	v_pk_mul_f32 v[42:43], v[42:43], v[68:69] op_sel_hi:[1,0]
	v_lshl_add_u64 v[66:67], v[74:75], 0, s[30:31]
	s_movk_i32 s30, 0x1000
	v_pk_mul_f32 v[36:37], v[36:37], v[68:69] op_sel_hi:[1,0]
	v_pk_mul_f32 v[34:35], v[34:35], v[68:69] op_sel_hi:[1,0]
	v_pk_mul_f32 v[40:41], v[40:41], v[68:69] op_sel_hi:[1,0]
	v_pk_mul_f32 v[38:39], v[38:39], v[68:69] op_sel_hi:[1,0]
	s_waitcnt vmcnt(0)
; __device__ __forceinline__ unsigned cvt_pk_bf16(float lo, float hi) { unsigned r; asm volatile("v_cvt_pk_bf16_f32 %0, %1, %2" : "=v"(r) : "v"(lo), "v"(hi)); return r; }
; __device__ __forceinline__ void attn_phase(LAS unsigned char* lds, bf16_t* p5, const bf16_t* vt, const float* relb, const float* dalam, const float* subln, float lam_init, int ocol) {
;     ...
;                     for (int k = 0; k < 8; ++k) { const f32x4 w = *(const f32x4*)(subln + 16 * k + 4 * g4); const f32x4 o = O[rg][k] * rn * w;
;                         *(u32x2*)(p5 + ((size_t)b * TP + q) * LDP + ocol + h * 128 + 16 * k + 4 * g4) = (u32x2){cvt_pk_bf16(o.x, o.y), cvt_pk_bf16(o.z, o.w)}; }
	v_pk_mul_f32 v[42:43], v[42:43], v[78:79]
	v_pk_mul_f32 v[44:45], v[44:45], v[76:77]
	s_nop 0
	v_cvt_pk_bf16_f32 v44, v44, v45
	v_cvt_pk_bf16_f32 v45, v42, v43
	v_add_co_u32_e32 v42, vcc, s30, v74
	s_nop 1
	v_addc_co_u32_e32 v43, vcc, 0, v75, vcc
	global_store_dwordx2 v[42:43], v[44:45], off
	s_nop 1
	s_nop 0
	v_pk_mul_f32 v[36:37], v[36:37], v[84:85]
	v_pk_mul_f32 v[34:35], v[34:35], v[86:87]
	v_cvt_pk_bf16_f32 v36, v36, v37
	s_nop 0
	v_cvt_pk_bf16_f32 v37, v34, v35
	global_store_dwordx2 v[66:67], v[36:37], off offset:32
	s_nop 1
	s_nop 0
	v_pk_mul_f32 v[34:35], v[40:41], v[96:97]
	v_pk_mul_f32 v[36:37], v[38:39], v[98:99]
	v_cvt_pk_bf16_f32 v34, v34, v35
	v_pk_mul_f32 v[38:39], v[48:49], v[68:69] op_sel_hi:[1,0]
	v_cvt_pk_bf16_f32 v35, v36, v37
	global_store_dwordx2 v[66:67], v[34:35], off offset:64
	s_nop 1
	v_pk_mul_f32 v[40:41], v[46:47], v[68:69] op_sel_hi:[1,0]
	s_nop 0
	v_pk_mul_f32 v[34:35], v[38:39], v[112:113]
	v_pk_mul_f32 v[36:37], v[40:41], v[114:115]
	v_cvt_pk_bf16_f32 v34, v34, v35
	v_pk_mul_f32 v[38:39], v[52:53], v[68:69] op_sel_hi:[1,0]
	v_cvt_pk_bf16_f32 v35, v36, v37
	global_store_dwordx2 v[66:67], v[34:35], off offset:96
	s_nop 1
	v_pk_mul_f32 v[40:41], v[50:51], v[68:69] op_sel_hi:[1,0]
	s_nop 0
	v_pk_mul_f32 v[34:35], v[38:39], v[116:117]
	v_pk_mul_f32 v[36:37], v[40:41], v[118:119]
	v_cvt_pk_bf16_f32 v34, v34, v35
	v_pk_mul_f32 v[38:39], v[56:57], v[68:69] op_sel_hi:[1,0]
	v_cvt_pk_bf16_f32 v35, v36, v37
	global_store_dwordx2 v[66:67], v[34:35], off offset:128
	s_nop 1
	v_pk_mul_f32 v[40:41], v[54:55], v[68:69] op_sel_hi:[1,0]
	s_nop 0
	v_pk_mul_f32 v[34:35], v[38:39], v[120:121]
	v_pk_mul_f32 v[36:37], v[40:41], v[122:123]
	v_cvt_pk_bf16_f32 v34, v34, v35
	v_pk_mul_f32 v[38:39], v[60:61], v[68:69] op_sel_hi:[1,0]
	v_cvt_pk_bf16_f32 v35, v36, v37
	global_store_dwordx2 v[66:67], v[34:35], off offset:160
	s_nop 1
	v_pk_mul_f32 v[40:41], v[58:59], v[68:69] op_sel_hi:[1,0]
	s_nop 0
	v_pk_mul_f32 v[34:35], v[38:39], v[124:125]
	v_pk_mul_f32 v[36:37], v[40:41], v[126:127]
	v_cvt_pk_bf16_f32 v34, v34, v35
	v_pk_mul_f32 v[38:39], v[64:65], v[68:69] op_sel_hi:[1,0]
	v_cvt_pk_bf16_f32 v35, v36, v37
	global_store_dwordx2 v[66:67], v[34:35], off offset:192
	s_nop 1
	v_pk_mul_f32 v[40:41], v[62:63], v[68:69] op_sel_hi:[1,0]
	s_nop 0
	v_pk_mul_f32 v[34:35], v[38:39], v[128:129]
	v_pk_mul_f32 v[36:37], v[40:41], v[130:131]
	v_cvt_pk_bf16_f32 v34, v34, v35
	s_nop 0
	v_cvt_pk_bf16_f32 v35, v36, v37
	global_store_dwordx2 v[66:67], v[34:35], off offset:224
; __device__ __forceinline__ unsigned cvt_pk_bf16(float lo, float hi) { unsigned r; asm volatile("v_cvt_pk_bf16_f32 %0, %1, %2" : "=v"(r) : "v"(lo), "v"(hi)); return r; }
; __device__ __forceinline__ void attn_phase(LAS unsigned char* lds, bf16_t* p5, const bf16_t* vt, const float* relb, const float* dalam, const float* subln, float lam_init, int ocol) {
;     ...
;             for (int rg = 0; rg < 2; ++rg) { const int q = qrow0 + 16 * rg + lq; float ss = 0.f;
; #pragma unroll
;                 for (int k = 0; k < 8; ++k) { O[rg][k] -= xch[(rg * 8 + k) * 64]; ss += (O[rg][k].x * O[rg][k].x + O[rg][k].y * O[rg][k].y) + (O[rg][k].z * O[rg][k].z + O[rg][k].w * O[rg][k].w); }
;                 ss = rows4_sum(ss);
;                 const float rn = rsqrtf(ss * (1.0f / 128.0f) + 1e-5f) * (1.0f - lam_init);
;                 if (q < TP) {
; #pragma unroll
;                     for (int k = 0; k < 8; ++k) { const f32x4 w = *(const f32x4*)(subln + 16 * k + 4 * g4); const f32x4 o = O[rg][k] * rn * w;
;                         *(u32x2*)(p5 + ((size_t)b * TP + q) * LDP + ocol + h * 128 + 16 * k + 4 * g4) = (u32x2){cvt_pk_bf16(o.x, o.y), cvt_pk_bf16(o.z, o.w)}; }
;                 }
.LBB0_786:
	s_or_b64 exec, exec, s[28:29]
	ds_read_b128 v[34:37], v197 offset:8192
	v_cmp_gt_i32_e32 vcc, s73, v166
	s_waitcnt lgkmcnt(0)
	v_sub_f32_e32 v33, v33, v37
	v_sub_f32_e32 v31, v31, v35
	v_sub_f32_e32 v32, v32, v36
	v_sub_f32_e32 v30, v30, v34
	v_mul_f32_e32 v34, v31, v31
	v_mul_f32_e32 v35, v33, v33
	v_fmac_f32_e32 v34, v30, v30
	v_fmac_f32_e32 v35, v32, v32
	v_add_f32_e32 v38, v34, v35
	ds_read_b128 v[34:37], v197 offset:9216
	s_waitcnt lgkmcnt(0)
	v_sub_f32_e32 v29, v29, v37
	v_sub_f32_e32 v27, v27, v35
	v_sub_f32_e32 v28, v28, v36
	v_sub_f32_e32 v26, v26, v34
	v_mul_f32_e32 v34, v27, v27
	v_mul_f32_e32 v35, v29, v29
	v_fmac_f32_e32 v34, v26, v26
	v_fmac_f32_e32 v35, v28, v28
	v_add_f32_e32 v34, v34, v35
	v_add_f32_e32 v38, v38, v34
	ds_read_b128 v[34:37], v197 offset:10240
	s_waitcnt lgkmcnt(0)
	v_sub_f32_e32 v25, v25, v37
	v_sub_f32_e32 v23, v23, v35
	v_sub_f32_e32 v24, v24, v36
	v_sub_f32_e32 v22, v22, v34
	v_mul_f32_e32 v34, v23, v23
	v_mul_f32_e32 v35, v25, v25
	v_fmac_f32_e32 v34, v22, v22
	v_fmac_f32_e32 v35, v24, v24
	v_add_f32_e32 v34, v34, v35
	v_add_f32_e32 v38, v38, v34
	ds_read_b128 v[34:37], v197 offset:11264
	s_waitcnt lgkmcnt(0)
	v_sub_f32_e32 v21, v21, v37
	v_sub_f32_e32 v19, v19, v35
	v_sub_f32_e32 v20, v20, v36
	v_sub_f32_e32 v18, v18, v34
	v_mul_f32_e32 v34, v19, v19
	v_mul_f32_e32 v35, v21, v21
	v_fmac_f32_e32 v34, v18, v18
	v_fmac_f32_e32 v35, v20, v20
	v_add_f32_e32 v34, v34, v35
	v_add_f32_e32 v38, v38, v34
	ds_read_b128 v[34:37], v197 offset:12288
	s_waitcnt lgkmcnt(0)
	v_sub_f32_e32 v17, v17, v37
	v_sub_f32_e32 v15, v15, v35
	v_sub_f32_e32 v16, v16, v36
	v_sub_f32_e32 v14, v14, v34
	v_mul_f32_e32 v34, v15, v15
	v_mul_f32_e32 v35, v17, v17
	v_fmac_f32_e32 v34, v14, v14
	v_fmac_f32_e32 v35, v16, v16
	v_add_f32_e32 v34, v34, v35
	v_add_f32_e32 v38, v38, v34
	ds_read_b128 v[34:37], v197 offset:13312
	s_waitcnt lgkmcnt(0)
	v_sub_f32_e32 v13, v13, v37
	v_sub_f32_e32 v11, v11, v35
	v_sub_f32_e32 v12, v12, v36
	v_sub_f32_e32 v10, v10, v34
	v_mul_f32_e32 v34, v11, v11
	v_mul_f32_e32 v35, v13, v13
	v_fmac_f32_e32 v34, v10, v10
	v_fmac_f32_e32 v35, v12, v12
	v_add_f32_e32 v34, v34, v35
	v_add_f32_e32 v38, v38, v34
	ds_read_b128 v[34:37], v197 offset:14336
	s_waitcnt lgkmcnt(0)
	v_sub_f32_e32 v9, v9, v37
	v_sub_f32_e32 v7, v7, v35
	v_sub_f32_e32 v8, v8, v36
	v_sub_f32_e32 v6, v6, v34
	v_mul_f32_e32 v34, v7, v7
	v_mul_f32_e32 v35, v9, v9
	v_fmac_f32_e32 v34, v6, v6
	v_fmac_f32_e32 v35, v8, v8
	v_add_f32_e32 v34, v34, v35
	v_add_f32_e32 v38, v38, v34
	ds_read_b128 v[34:37], v197 offset:15360
	s_waitcnt lgkmcnt(0)
	v_sub_f32_e32 v5, v5, v37
	v_sub_f32_e32 v3, v3, v35
	v_sub_f32_e32 v4, v4, v36
	v_sub_f32_e32 v2, v2, v34
	v_mul_f32_e32 v34, v3, v3
	v_mul_f32_e32 v35, v5, v5
	v_fmac_f32_e32 v34, v2, v2
	v_fmac_f32_e32 v35, v4, v4
	v_add_f32_e32 v34, v34, v35
	v_add_f32_e32 v34, v38, v34
	v_mov_b32_e32 v35, v34
	s_nop 1
	v_permlane16_swap_b32_e32 v34, v35
	v_add_f32_e32 v34, v34, v35
	v_mov_b32_e32 v35, v34
	s_nop 1
	v_permlane32_swap_b32_e32 v34, v35
	s_and_saveexec_b64 s[28:29], vcc
	s_cbranch_execz .LBB0_788
	v_add_f32_e32 v34, v34, v35
	v_mov_b32_e32 v35, 0x3727c5ac
	v_fmamk_f32 v34, v34, 0x3c000000, v35
	s_mov_b32 s30, 0x800000
	v_cmp_gt_f32_e32 vcc, s30, v34
	v_mul_f32_e32 v35, 0x4b800000, v34
	v_ashrrev_i32_e32 v167, 31, v166
	v_cndmask_b32_e32 v34, v34, v35, vcc
	v_rsq_f32_e32 v34, v34
	v_mov_b64_e32 v[38:39], s[4:5]
	s_lshl_b32 s68, s19, 1
	s_movk_i32 s19, 0x1000
	v_mul_f32_e32 v35, 0x45800000, v34
	v_cndmask_b32_e32 v34, v34, v35, vcc
	v_mul_f32_e32 v36, v178, v34
	v_lshl_add_u64 v[34:35], v[166:167], 0, s[24:25]
	v_mad_u64_u32 v[38:39], s[24:25], v34, s84, v[38:39]
	v_mad_i32_i24 v39, v35, s84, v39
	v_lshl_add_u64 v[34:35], v[38:39], 0, s[68:69]
	s_nop 1
	v_pk_mul_f32 v[30:31], v[30:31], v[36:37] op_sel_hi:[1,0]
	v_pk_mul_f32 v[32:33], v[32:33], v[36:37] op_sel_hi:[1,0]
	v_lshl_add_u64 v[42:43], v[34:35], 0, v[0:1]
	s_mov_b64 s[24:25], 0x1000
	v_pk_mul_f32 v[26:27], v[26:27], v[36:37] op_sel_hi:[1,0]
	v_lshl_add_u64 v[34:35], v[42:43], 0, s[24:25]
	v_pk_mul_f32 v[28:29], v[28:29], v[36:37] op_sel_hi:[1,0]
	v_pk_mul_f32 v[22:23], v[22:23], v[36:37] op_sel_hi:[1,0]
	v_pk_mul_f32 v[24:25], v[24:25], v[36:37] op_sel_hi:[1,0]
	v_pk_mul_f32 v[18:19], v[18:19], v[36:37] op_sel_hi:[1,0]
	v_pk_mul_f32 v[20:21], v[20:21], v[36:37] op_sel_hi:[1,0]
	v_pk_mul_f32 v[14:15], v[14:15], v[36:37] op_sel_hi:[1,0]
	v_pk_mul_f32 v[16:17], v[16:17], v[36:37] op_sel_hi:[1,0]
	v_pk_mul_f32 v[10:11], v[10:11], v[36:37] op_sel_hi:[1,0]
	v_pk_mul_f32 v[12:13], v[12:13], v[36:37] op_sel_hi:[1,0]
	v_pk_mul_f32 v[6:7], v[6:7], v[36:37] op_sel_hi:[1,0]
	v_pk_mul_f32 v[8:9], v[8:9], v[36:37] op_sel_hi:[1,0]
	v_pk_mul_f32 v[2:3], v[2:3], v[36:37] op_sel_hi:[1,0]
	v_pk_mul_f32 v[4:5], v[4:5], v[36:37] op_sel_hi:[1,0]
	s_waitcnt vmcnt(0)
	v_pk_mul_f32 v[32:33], v[32:33], v[78:79]
	v_pk_mul_f32 v[30:31], v[30:31], v[76:77]
	s_nop 0
	v_cvt_pk_bf16_f32 v30, v30, v31
	v_cvt_pk_bf16_f32 v31, v32, v33
	v_add_co_u32_e32 v32, vcc, s19, v42
	s_nop 1
	v_addc_co_u32_e32 v33, vcc, 0, v43, vcc
	global_store_dwordx2 v[32:33], v[30:31], off
	s_nop 1
	s_nop 0
	v_pk_mul_f32 v[26:27], v[26:27], v[84:85]
	v_pk_mul_f32 v[28:29], v[28:29], v[86:87]
	v_cvt_pk_bf16_f32 v26, v26, v27
	s_nop 0
	v_cvt_pk_bf16_f32 v27, v28, v29
	global_store_dwordx2 v[34:35], v[26:27], off offset:32
	s_nop 1
	s_nop 0
	v_pk_mul_f32 v[22:23], v[22:23], v[96:97]
	v_pk_mul_f32 v[24:25], v[24:25], v[98:99]
	v_cvt_pk_bf16_f32 v22, v22, v23
	s_nop 0
	v_cvt_pk_bf16_f32 v23, v24, v25
	global_store_dwordx2 v[34:35], v[22:23], off offset:64
	s_nop 1
	s_nop 0
	v_pk_mul_f32 v[18:19], v[18:19], v[112:113]
	v_pk_mul_f32 v[20:21], v[20:21], v[114:115]
	v_cvt_pk_bf16_f32 v18, v18, v19
	s_nop 0
	v_cvt_pk_bf16_f32 v19, v20, v21
	global_store_dwordx2 v[34:35], v[18:19], off offset:96
	s_nop 1
	s_nop 0
	v_pk_mul_f32 v[14:15], v[14:15], v[116:117]
	v_pk_mul_f32 v[16:17], v[16:17], v[118:119]
	v_cvt_pk_bf16_f32 v14, v14, v15
	s_nop 0
	v_cvt_pk_bf16_f32 v15, v16, v17
	global_store_dwordx2 v[34:35], v[14:15], off offset:128
	s_nop 1
	s_nop 0
	v_pk_mul_f32 v[10:11], v[10:11], v[120:121]
	v_pk_mul_f32 v[12:13], v[12:13], v[122:123]
	v_cvt_pk_bf16_f32 v10, v10, v11
	s_nop 0
	v_cvt_pk_bf16_f32 v11, v12, v13
	global_store_dwordx2 v[34:35], v[10:11], off offset:160
	s_nop 1
	s_nop 0
	v_pk_mul_f32 v[6:7], v[6:7], v[124:125]
	v_pk_mul_f32 v[8:9], v[8:9], v[126:127]
	v_cvt_pk_bf16_f32 v6, v6, v7
	s_nop 0
	v_cvt_pk_bf16_f32 v7, v8, v9
	global_store_dwordx2 v[34:35], v[6:7], off offset:192
	s_nop 1
	s_nop 0
	v_pk_mul_f32 v[2:3], v[2:3], v[128:129]
	v_pk_mul_f32 v[4:5], v[4:5], v[130:131]
	v_cvt_pk_bf16_f32 v2, v2, v3
	s_nop 0
	v_cvt_pk_bf16_f32 v3, v4, v5
	global_store_dwordx2 v[34:35], v[2:3], off offset:224
